# rwkv_post per-head loop fetches all its global operands for both token halves in one batch
# speedup vs baseline: 1.0158x; 1.0068x over previous
; __device__ void rwkv_post_phase(const Params& p, int l, LAS unsigned char* lds) {
;     ...
;             for (int tl = 0; tl < ntl; ++tl) {
;                 const size_t t0 = (size_t)(base + tl * NBLK()) * 64;
;                 __syncthreads();
; #pragma unroll
;                 for (int i = 0; i < 2; ++i) { const int id = wid + 8 * i, rt = id >> 2, ct = id & 3; const f32x4 z4 = {0.f, 0.f, 0.f, 0.f};
;                     const f32x4 acc = mm_nt<3>(sgb + tl * 6656, 104, rt * 16, g2T + h * 64 * 104, 104, ct * 16, r16, quad, z4);
; #pragma unroll
;                     for (int j = 0; j < 4; ++j) gs[(rt * 16 + quad * 4 + j) * 64 + ct * 16 + r16] = acc[j]; }
;                 __syncthreads();
;                 const f32x4 gA = *(const LAS f32x4*)(gs + tp * 64 + cg * 4), gB = *(const LAS f32x4*)(gs + (tp + 32) * 64 + cg * 4);
; #pragma unroll
;                 for (int which = 0; which < 2; ++which) {
;                     const size_t t = t0 + tp + which * 32; const int s = (int)(t & (SEQ_ - 1));
;                     const u32x2 yfr = *(const u32x2*)(YF + t * 512 + c), ybr = *(const u32x2*)(YBk + t * 512 + c);
;                     f32x4 y; y[0] = bf_lo(yfr.x) + bf_lo(ybr.x); y[1] = bf_hi(yfr.x) + bf_hi(ybr.x); y[2] = bf_lo(yfr.y) + bf_lo(ybr.y); y[3] = bf_hi(yfr.y) + bf_hi(ybr.y);
;                     const float mean = red16d(y[0] + y[1] + y[2] + y[3]) * (1.0f / 64.0f);
;                     const f32x4 d = y - mean;
;                     const float var = red16d(d[0] * d[0] + d[1] * d[1] + d[2] * d[2] + d[3] * d[3]) * (1.0f / 64.0f);
;                     const float rs = rsqrtf(var + 64e-5f);
;                     const bf16_t* zp = ZR + t * ZRC + 1024 + c;
;                     const u32x2 vc = *(const u32x2*)zp; u32x2 vp = {0u, 0u}, vn = {0u, 0u};
;                     if (s > 0) vp = *(const u32x2*)(zp - ZRC);
;                     if (s < SEQ_ - 1) vn = *(const u32x2*)(zp + ZRC);
;                     f32x4 vcur, vprev, vnext;
;                     vcur[0] = bf_lo(vc.x); vcur[1] = bf_hi(vc.x); vcur[2] = bf_lo(vc.y); vcur[3] = bf_hi(vc.y);
;                     vprev[0] = bf_lo(vp.x); vprev[1] = bf_hi(vp.x); vprev[2] = bf_lo(vp.y); vprev[3] = bf_hi(vp.y);
;                     vnext[0] = bf_lo(vn.x); vnext[1] = bf_hi(vn.x); vnext[2] = bf_lo(vn.y); vnext[3] = bf_hi(vn.y);
;                     const f32x4 vs = vcur + m4 * ((vprev + vnext) * 0.5f - vcur);
.LBB0_214:
	s_or_b64 exec, exec, s[20:21]
	v_lshlrev_b64 v[20:21], 5, v[20:21]
	v_lshl_add_u64 v[20:21], s[18:19], 0, v[20:21]
	v_mov_b32_e32 v0, v75
	v_add_f32_e32 v46, v45, v46
	v_lshlrev_b32_e32 v20, 16, v38
	v_and_b32_e32 v21, 0xffff0000, v38
	v_lshlrev_b32_e32 v42, 16, v40
	v_and_b32_e32 v43, 0xffff0000, v40
	v_lshlrev_b32_e32 v40, 16, v41
	v_and_b32_e32 v41, 0xffff0000, v41
	v_lshlrev_b32_e32 v44, 16, v32
	v_and_b32_e32 v45, 0xffff0000, v32
	v_lshlrev_b32_e32 v32, 16, v33
	v_and_b32_e32 v33, 0xffff0000, v33
	v_fmamk_f32 v46, v46, 0x3c800000, v170
	v_pk_add_f32 v[32:33], v[40:41], v[32:33]
	v_pk_add_f32 v[40:41], v[42:43], v[44:45]
	v_xor_b32_e32 v43, 0x80000000, v21
	v_xor_b32_e32 v42, 0x80000000, v20
	v_mul_f32_e32 v47, 0x4b800000, v46
	v_cmp_gt_f32_e32 vcc, s33, v46
	v_pk_fma_f32 v[40:41], v[40:41], 0.5, v[42:43] op_sel_hi:[1,0,1]
	v_lshlrev_b32_e32 v38, 16, v39
	v_cndmask_b32_e32 v42, v46, v47, vcc
	v_rsq_f32_e32 v42, v42
	v_and_b32_e32 v39, 0xffff0000, v39
	v_xor_b32_e32 v45, 0x80000000, v39
	v_xor_b32_e32 v44, 0x80000000, v38
	v_pk_fma_f32 v[32:33], v[32:33], 0.5, v[44:45] op_sel_hi:[1,0,1]
	v_pk_fma_f32 v[20:21], v[10:11], v[40:41], v[20:21]
	v_pk_fma_f32 v[32:33], v[12:13], v[32:33], v[38:39]
	v_mul_f32_e32 v38, 0x45800000, v42
	v_cndmask_b32_e32 v38, v42, v38, vcc
	v_pk_mul_f32 v[34:35], v[34:35], v[38:39] op_sel_hi:[1,0]
	v_pk_mul_f32 v[36:37], v[36:37], v[38:39] op_sel_hi:[1,0]
	v_pk_fma_f32 v[34:35], v[2:3], v[34:35], v[6:7]
	v_pk_fma_f32 v[36:37], v[4:5], v[36:37], v[8:9]
	s_add_i32 s22, s22, 1
	s_cmp_eq_u32 s41, s22
	v_add_u32_e32 v57, 0x3400, v57
	v_pk_fma_f32 v[20:21], v[0:1], v[20:21], v[34:35] op_sel_hi:[0,1,1]
	v_pk_fma_f32 v[32:33], v[0:1], v[32:33], v[36:37] op_sel_hi:[0,1,1]
	v_pk_mul_f32 v[16:17], v[16:17], v[32:33]
	v_pk_mul_f32 v[14:15], v[14:15], v[20:21]
	s_nop 0
	v_cvt_pk_bf16_f32 v14, v14, v15
	v_cvt_pk_bf16_f32 v15, v16, v17
	global_store_dwordx2 v[18:19], v[14:15], off
	s_cbranch_scc1 .LBB0_212
.LBB0_215:
	s_mov_b32 s20, s39
	s_waitcnt lgkmcnt(0)
	s_barrier
	ds_read_b128 v[14:17], v57
	ds_read_b128 v[18:21], v27
	s_waitcnt lgkmcnt(0)
	v_mfma_f32_16x16x32_bf16 v[14:17], v[14:17], v[18:21], 0
	ds_read_b128 v[18:21], v57 offset:64
	ds_read_b128 v[32:35], v27 offset:64
	v_add_u32_e32 v0, v51, v53
	s_mul_i32 s20, s20, s22
	s_waitcnt lgkmcnt(0)
	v_mfma_f32_16x16x32_bf16 v[14:17], v[18:21], v[32:35], v[14:17]
	ds_read_b128 v[18:21], v57 offset:128
	ds_read_b128 v[32:35], v27 offset:128
	s_add_i32 s20, s20, s34
	s_ashr_i32 s21, s20, 31
	s_waitcnt lgkmcnt(0)
	v_mfma_f32_16x16x32_bf16 v[14:17], v[18:21], v[32:35], v[14:17]
	s_nop 7
	ds_write2st64_b32 v0, v14, v15 offset1:1
	ds_write2st64_b32 v0, v16, v17 offset0:2 offset1:3
	ds_read_b128 v[14:17], v57 offset:6656
	ds_read_b128 v[18:21], v27
	s_waitcnt lgkmcnt(0)
	v_mfma_f32_16x16x32_bf16 v[14:17], v[14:17], v[18:21], 0
	ds_read_b128 v[18:21], v57 offset:6720
	ds_read_b128 v[32:35], v27 offset:64
	s_lshl_b64 s[20:21], s[20:21], 6
	v_mov_b32_e32 v42, 0
	s_waitcnt lgkmcnt(0)
	v_mfma_f32_16x16x32_bf16 v[14:17], v[18:21], v[32:35], v[14:17]
	ds_read_b128 v[18:21], v57 offset:6784
	ds_read_b128 v[32:35], v27 offset:128
	v_mov_b32_e32 v48, 0
	v_mov_b32_e32 v49, 0
	s_waitcnt lgkmcnt(0)
	v_mfma_f32_16x16x32_bf16 v[14:17], v[18:21], v[32:35], v[14:17]
	v_lshl_add_u64 v[34:35], s[20:21], 0, v[24:25]
	v_lshlrev_b64 v[32:33], 10, v[34:35]
	v_lshl_add_u64 v[36:37], v[28:29], 0, v[32:33]
	v_lshl_add_u64 v[32:33], v[30:31], 0, v[32:33]
	v_add_co_u32_e32 v86, vcc, 0x8000, v36
	s_nop 1
	v_addc_co_u32_e32 v87, vcc, 0, v37, vcc
	v_add_co_u32_e32 v88, vcc, 0x8000, v32
	s_nop 1
	v_addc_co_u32_e32 v89, vcc, 0, v33, vcc
	v_mov_b64_e32 v[90:91], s[4:5]
	v_mad_u64_u32 v[90:91], vcc, v34, s46, v[90:91]
	v_mad_i32_i24 v91, v35, s46, v91
	v_lshlrev_b32_e32 v92, 1, v26
	v_mov_b32_e32 v93, 0
	v_lshl_add_u64 v[90:91], v[90:91], 0, v[92:93]
	v_lshl_add_u64 v[90:91], v[90:91], 0, s[36:37]
	v_add_co_u32_e32 v94, vcc, 0x1b800, v90
	s_nop 1
	v_addc_co_u32_e32 v95, vcc, 0, v91, vcc
	v_lshlrev_b64 v[96:97], 5, v[34:35]
	v_lshl_add_u64 v[96:97], s[18:19], 0, v[96:97]
	global_load_dwordx2 v[40:41], v[36:37], off
	global_load_dwordx2 v[32:33], v[32:33], off
	global_load_dwordx2 v[68:69], v[90:91], off
	global_load_dwordx2 v[70:71], v[90:91], off offset:-3520
	global_load_dwordx2 v[72:73], v[90:91], off offset:3520
	global_load_dword v74, v[96:97], off
	global_load_dwordx2 v[76:77], v[86:87], off
	global_load_dwordx2 v[78:79], v[88:89], off
	global_load_dwordx2 v[80:81], v[94:95], off
	global_load_dwordx2 v[82:83], v[94:95], off offset:-3520
	global_load_dwordx2 v[84:85], v[94:95], off offset:3520
	global_load_dword v75, v[96:97], off offset:1024
	s_nop 3
	ds_write2st64_b32 v56, v14, v15 offset1:1
	ds_write2st64_b32 v56, v16, v17 offset0:2 offset1:3
	s_waitcnt lgkmcnt(0)
	s_barrier
	ds_read_b128 v[18:21], v52
	ds_read_b128 v[14:17], v52 offset:8192
	v_and_b32_e32 v43, 0x7ff, v34
	v_cmp_ne_u32_e32 vcc, 0, v43
	s_waitcnt vmcnt(0) lgkmcnt(0)
	v_lshlrev_b32_e32 v38, 16, v40
	v_and_b32_e32 v39, 0xffff0000, v40
	v_lshlrev_b32_e32 v44, 16, v32
	v_and_b32_e32 v45, 0xffff0000, v32
	v_pk_add_f32 v[38:39], v[38:39], v[44:45]
	v_lshlrev_b32_e32 v40, 16, v41
	v_and_b32_e32 v41, 0xffff0000, v41
	v_lshlrev_b32_e32 v32, 16, v33
	v_and_b32_e32 v33, 0xffff0000, v33
	v_pk_add_f32 v[40:41], v[40:41], v[32:33]
	v_add_f32_e32 v0, v38, v39
	v_add_f32_e32 v0, v40, v0
	v_add_f32_e32 v0, v41, v0
	s_nop 1
	v_add_f32_dpp v0, v0, v0 quad_perm:[1,0,3,2] row_mask:0xf bank_mask:0xf bound_ctrl:1
	s_nop 1
	v_add_f32_dpp v0, v0, v0 quad_perm:[2,3,0,1] row_mask:0xf bank_mask:0xf bound_ctrl:1
	s_nop 1
	v_add_f32_dpp v0, v0, v0 row_half_mirror row_mask:0xf bank_mask:0xf bound_ctrl:1
	s_nop 1
	v_add_f32_dpp v0, v0, v0 row_mirror row_mask:0xf bank_mask:0xf bound_ctrl:1
	v_fmamk_f32 v39, v0, 0xbc800000, v39
	v_fmac_f32_e32 v38, 0xbc800000, v0
	v_fmamk_f32 v41, v0, 0xbc800000, v41
	v_fmac_f32_e32 v40, 0xbc800000, v0
	v_pk_mul_f32 v[44:45], v[38:39], v[38:39]
	v_pk_mul_f32 v[32:33], v[40:41], v[40:41]
	v_add_f32_e32 v0, v44, v45
	v_add_f32_e32 v0, v32, v0
	v_add_f32_e32 v0, v33, v0
	v_mov_b64_e32 v[32:33], s[4:5]
	v_mad_u64_u32 v[32:33], s[20:21], v34, s46, v[32:33]
	v_add_f32_dpp v0, v0, v0 quad_perm:[1,0,3,2] row_mask:0xf bank_mask:0xf bound_ctrl:1
	v_mad_i32_i24 v33, v35, s46, v33
	s_nop 0
	v_add_f32_dpp v0, v0, v0 quad_perm:[2,3,0,1] row_mask:0xf bank_mask:0xf bound_ctrl:1
	s_nop 1
	v_add_f32_dpp v58, v0, v0 row_half_mirror row_mask:0xf bank_mask:0xf bound_ctrl:1
	v_lshlrev_b32_e32 v0, 1, v26
	v_lshl_add_u64 v[44:45], v[32:33], 0, v[0:1]
	v_lshl_add_u64 v[46:47], v[44:45], 0, s[36:37]
	v_mov_b64_e32 v[44:45], v[68:69]
	v_mov_b32_dpp v59, v58 row_mirror row_mask:0xf bank_mask:0xf bound_ctrl:1
	s_and_saveexec_b64 s[20:21], vcc
	s_cbranch_execz .LBB0_217
	v_add_co_u32_e32 v48, vcc, 0xfffff240, v46
	s_nop 1
	v_addc_co_u32_e32 v49, vcc, -1, v47, vcc
	v_mov_b64_e32 v[48:49], v[70:71]
; __device__ __forceinline__ unsigned cvt_pk_bf16(float lo, float hi) { const f32x2_t v = {lo, hi}; const bf16x2_t b = __builtin_convertvector(v, bf16x2_t); return __builtin_bit_cast(unsigned, b); }
; __device__ __forceinline__ float bf_lo(unsigned w) { return __uint_as_float(w << 16); }
; __device__ __forceinline__ float bf_hi(unsigned w) { return __uint_as_float(w & 0xffff0000u); }
; __device__ void rwkv_post_phase(const Params& p, int l, LAS unsigned char* lds) {
;     ...
;                 for (int which = 0; which < 2; ++which) {
;                     const size_t t = t0 + tp + which * 32; const int s = (int)(t & (SEQ_ - 1));
;                     const u32x2 yfr = *(const u32x2*)(YF + t * 512 + c), ybr = *(const u32x2*)(YBk + t * 512 + c);
;                     f32x4 y; y[0] = bf_lo(yfr.x) + bf_lo(ybr.x); y[1] = bf_hi(yfr.x) + bf_hi(ybr.x); y[2] = bf_lo(yfr.y) + bf_lo(ybr.y); y[3] = bf_hi(yfr.y) + bf_hi(ybr.y);
;                     const float mean = red16d(y[0] + y[1] + y[2] + y[3]) * (1.0f / 64.0f);
;                     const f32x4 d = y - mean;
;                     const float var = red16d(d[0] * d[0] + d[1] * d[1] + d[2] * d[2] + d[3] * d[3]) * (1.0f / 64.0f);
;                     const float rs = rsqrtf(var + 64e-5f);
;                     const bf16_t* zp = ZR + t * ZRC + 1024 + c;
;                     const u32x2 vc = *(const u32x2*)zp; u32x2 vp = {0u, 0u}, vn = {0u, 0u};
;                     if (s > 0) vp = *(const u32x2*)(zp - ZRC);
;                     if (s < SEQ_ - 1) vn = *(const u32x2*)(zp + ZRC);
;                     f32x4 vcur, vprev, vnext;
;                     vcur[0] = bf_lo(vc.x); vcur[1] = bf_hi(vc.x); vcur[2] = bf_lo(vc.y); vcur[3] = bf_hi(vc.y);
;                     vprev[0] = bf_lo(vp.x); vprev[1] = bf_hi(vp.x); vprev[2] = bf_lo(vp.y); vprev[3] = bf_hi(vp.y);
;                     vnext[0] = bf_lo(vn.x); vnext[1] = bf_hi(vn.x); vnext[2] = bf_lo(vn.y); vnext[3] = bf_hi(vn.y);
;                     const f32x4 vs = vcur + m4 * ((vprev + vnext) * 0.5f - vcur);
;                     const float bon = BON[t * 8 + h];
;                     const f32x4 gg = which ? gB : gA;
;                     const f32x4 o = (d * rs * lg + lb + vs * bon) * gg;
;                     u32x2 ow; ow.x = cvt_pk_bf16(o[0], o[1]); ow.y = cvt_pk_bf16(o[2], o[3]);
;                     *(u32x2*)(YF + t * 512 + c) = ow;
.LBB0_217:
	s_or_b64 exec, exec, s[20:21]
	v_cmp_ne_u32_e32 vcc, s75, v43
	v_mov_b32_e32 v43, 0
	s_and_saveexec_b64 s[20:21], vcc
	s_cbranch_execz .LBB0_219
	v_mov_b64_e32 v[42:43], v[72:73]
.LBB0_219:
	s_or_b64 exec, exec, s[20:21]
	v_add_f32_e32 v46, v58, v59
	v_lshlrev_b32_e32 v58, 16, v44
	v_and_b32_e32 v59, 0xffff0000, v44
	v_lshlrev_b32_e32 v60, 16, v48
	v_and_b32_e32 v61, 0xffff0000, v48
	v_lshlrev_b32_e32 v48, 16, v49
	v_and_b32_e32 v49, 0xffff0000, v49
	v_lshlrev_b32_e32 v62, 16, v42
	v_and_b32_e32 v63, 0xffff0000, v42
	v_lshlrev_b32_e32 v42, 16, v43
	v_and_b32_e32 v43, 0xffff0000, v43
	v_lshlrev_b32_e32 v44, 16, v45
	v_and_b32_e32 v45, 0xffff0000, v45
	v_pk_add_f32 v[42:43], v[48:49], v[42:43]
	v_pk_add_f32 v[48:49], v[60:61], v[62:63]
	v_xor_b32_e32 v61, 0x80000000, v59
	v_xor_b32_e32 v60, 0x80000000, v58
	v_pk_fma_f32 v[48:49], v[48:49], 0.5, v[60:61] op_sel_hi:[1,0,1]
	v_xor_b32_e32 v61, 0x80000000, v45
	v_xor_b32_e32 v60, 0x80000000, v44
	v_pk_fma_f32 v[42:43], v[42:43], 0.5, v[60:61] op_sel_hi:[1,0,1]
	v_fmamk_f32 v46, v46, 0x3c800000, v170
	v_pk_fma_f32 v[42:43], v[12:13], v[42:43], v[44:45]
	v_pk_fma_f32 v[44:45], v[10:11], v[48:49], v[58:59]
	v_lshlrev_b64 v[48:49], 5, v[34:35]
	v_lshl_add_u64 v[48:49], s[18:19], 0, v[48:49]
	v_mov_b32_e32 v48, v74
	v_cmp_gt_f32_e32 vcc, s33, v46
	v_mul_f32_e32 v47, 0x4b800000, v46
	v_lshl_add_u64 v[32:33], v[32:33], 0, v[0:1]
	v_cndmask_b32_e32 v46, v46, v47, vcc
	v_rsq_f32_e32 v46, v46
	s_mov_b64 s[20:21], 0x1c000
	v_mul_f32_e32 v47, 0x45800000, v46
	v_cndmask_b32_e32 v46, v46, v47, vcc
	v_pk_mul_f32 v[38:39], v[38:39], v[46:47] op_sel_hi:[1,0]
	v_pk_mul_f32 v[40:41], v[40:41], v[46:47] op_sel_hi:[1,0]
	v_pk_fma_f32 v[38:39], v[2:3], v[38:39], v[6:7]
	v_pk_fma_f32 v[40:41], v[4:5], v[40:41], v[8:9]
	v_pk_fma_f32 v[38:39], v[48:49], v[44:45], v[38:39] op_sel_hi:[0,1,1]
	v_pk_fma_f32 v[40:41], v[48:49], v[42:43], v[40:41] op_sel_hi:[0,1,1]
	v_pk_mul_f32 v[20:21], v[20:21], v[40:41]
	v_pk_mul_f32 v[18:19], v[18:19], v[38:39]
	v_lshl_add_u64 v[42:43], v[32:33], 0, s[20:21]
	v_cvt_pk_bf16_f32 v18, v18, v19
	v_cvt_pk_bf16_f32 v19, v20, v21
	v_lshl_add_u64 v[20:21], v[34:35], 0, 32
	v_lshlrev_b64 v[34:35], 10, v[20:21]
	global_store_dwordx2 v[36:37], v[18:19], off
	v_lshl_add_u64 v[18:19], v[28:29], 0, v[34:35]
	v_lshl_add_u64 v[34:35], v[30:31], 0, v[34:35]
	v_mov_b64_e32 v[36:37], v[76:77]
	v_mov_b64_e32 v[38:39], v[78:79]
	v_add_co_u32_e32 v32, vcc, 0x1c000, v32
	v_and_b32_e32 v44, 0x7ff, v20
	s_nop 0
	v_addc_co_u32_e32 v33, vcc, 0, v33, vcc
	v_cmp_ne_u32_e32 vcc, 0, v44
	v_lshlrev_b32_e32 v34, 16, v36
	v_and_b32_e32 v35, 0xffff0000, v36
	v_lshlrev_b32_e32 v40, 16, v38
	v_and_b32_e32 v41, 0xffff0000, v38
	v_pk_add_f32 v[34:35], v[34:35], v[40:41]
	v_lshlrev_b32_e32 v36, 16, v37
	v_and_b32_e32 v37, 0xffff0000, v37
	v_lshlrev_b32_e32 v38, 16, v39
	v_and_b32_e32 v39, 0xffff0000, v39
	v_pk_add_f32 v[36:37], v[36:37], v[38:39]
	v_add_f32_e32 v38, v34, v35
	v_add_f32_e32 v38, v36, v38
	v_add_f32_e32 v38, v37, v38
	s_nop 1
	v_add_f32_dpp v38, v38, v38 quad_perm:[1,0,3,2] row_mask:0xf bank_mask:0xf bound_ctrl:1
	s_nop 1
	v_add_f32_dpp v38, v38, v38 quad_perm:[2,3,0,1] row_mask:0xf bank_mask:0xf bound_ctrl:1
	s_nop 1
	v_add_f32_dpp v38, v38, v38 row_half_mirror row_mask:0xf bank_mask:0xf bound_ctrl:1
	s_nop 1
	v_add_f32_dpp v38, v38, v38 row_mirror row_mask:0xf bank_mask:0xf bound_ctrl:1
	v_fmamk_f32 v35, v38, 0xbc800000, v35
	v_fmac_f32_e32 v34, 0xbc800000, v38
	v_fmamk_f32 v37, v38, 0xbc800000, v37
	v_fmac_f32_e32 v36, 0xbc800000, v38
	v_pk_mul_f32 v[40:41], v[34:35], v[34:35]
	v_pk_mul_f32 v[38:39], v[36:37], v[36:37]
	v_add_f32_e32 v40, v40, v41
	v_add_f32_e32 v38, v38, v40
	v_add_f32_e32 v38, v39, v38
	v_mov_b32_e32 v40, 0
	v_mov_b32_e32 v41, 0
	v_add_f32_dpp v38, v38, v38 quad_perm:[1,0,3,2] row_mask:0xf bank_mask:0xf bound_ctrl:1
	s_nop 1
	v_add_f32_dpp v38, v38, v38 quad_perm:[2,3,0,1] row_mask:0xf bank_mask:0xf bound_ctrl:1
	s_nop 1
	v_add_f32_dpp v45, v38, v38 row_half_mirror row_mask:0xf bank_mask:0xf bound_ctrl:1
	v_mov_b64_e32 v[38:39], v[80:81]
	v_mov_b32_e32 v32, 0
	v_mov_b32_dpp v46, v45 row_mirror row_mask:0xf bank_mask:0xf bound_ctrl:1
	s_and_saveexec_b64 s[20:21], vcc
	s_cbranch_execz .LBB0_221
	v_add_co_u32_e32 v40, vcc, 0xfffff240, v42
	s_nop 1
	v_addc_co_u32_e32 v41, vcc, -1, v43, vcc
	v_mov_b64_e32 v[40:41], v[82:83]
.LBB0_221:
	s_or_b64 exec, exec, s[20:21]
	v_cmp_ne_u32_e32 vcc, s75, v44
	v_mov_b32_e32 v33, 0
	s_and_saveexec_b64 s[20:21], vcc
	s_cbranch_execz .LBB0_214
	v_mov_b64_e32 v[32:33], v[84:85]
	s_branch .LBB0_214
